# v25 + every workgroup issues buffer_wbl2 sc1 when it arrives at a grid barrier (early cooperative L2 write-back; the XCD leader's release flush is kept)
# baseline (speedup 1.0000x reference)
; __device__ __forceinline__ unsigned xb_ld(unsigned* p)              { return __hip_atomic_load(p, __ATOMIC_RELAXED, __HIP_MEMORY_SCOPE_AGENT); }
; __device__ __forceinline__ unsigned xb_add(unsigned* p, unsigned v) { return __hip_atomic_fetch_add(p, v, __ATOMIC_RELAXED, __HIP_MEMORY_SCOPE_AGENT); }
; __device__ __forceinline__ void xcd_barrier_complete(unsigned* bar, unsigned x, unsigned& nloc, unsigned& nx) {
;     const unsigned G = gridDim.x * gridDim.y * gridDim.z;
;     unsigned sum, cnt, mine, sp = 0u;
;     for (;;) {
;         sum = 0u; cnt = 0u; mine = 0u;
; #pragma unroll
;         for (unsigned j = 0; j < 16; ++j) { const unsigned c = xb_ld(&bar[XB_XCNT(j)]); sum += c; cnt += (c > 0u) ? 1u : 0u; mine = (j == x) ? c : mine; }
; __device__ __forceinline__ void xcd_barrier(const XcdBarrier& b) {
;     asm volatile("s_waitcnt vmcnt(0)" ::: "memory");
;     __syncthreads();
;     if (threadIdx.x == 0) {
;         unsigned* bar = b.bar;
;         __builtin_amdgcn_s_waitcnt(0);
;         unsigned nloc = b.st[0], nx = b.st[1];
;         if (nloc == 0u) { xcd_barrier_complete(bar, b.x, nloc, nx); b.st[0] = nloc; b.st[1] = nx; }
;         const unsigned old = xb_add(&bar[XB_XSUB(b.x)], 1u);
.LBB0_119:
	v_mov_b32_e32 v0, 0
	s_nop 0
	v_add_u32_e32 v0, 0, v0
	v_add_u32_e32 v0, 0x200c8, v0
	s_waitcnt lgkmcnt(0)
	ds_read_b64 v[0:1], v0
	s_getreg_b32 s0, hwreg(HW_REG_XCC_ID, 0, 4)
	s_waitcnt vmcnt(0)
	s_waitcnt lgkmcnt(0)
	s_barrier
	v_readfirstlane_b32 s3, v1
	v_readfirstlane_b32 s11, v0
	s_mov_b64 s[36:37], exec
	v_readlane_b32 s4, v255, 1
	v_readlane_b32 s5, v255, 2
	s_and_b64 s[4:5], s[36:37], s[4:5]
	s_mov_b64 exec, s[4:5]
	s_cbranch_execz .LBB0_163
	buffer_wbl2 sc1
	s_add_i32 s1, 0, 0x20200
	v_mov_b32_e32 v0, s1
	s_waitcnt vmcnt(0) expcnt(0) lgkmcnt(0)
	ds_read_b32 v2, v0
	s_add_i32 s1, 0, 0x20204
	v_mov_b32_e32 v0, s1
	ds_read_b32 v0, v0
	s_and_b32 s33, s0, 15
	s_waitcnt lgkmcnt(1)
	v_cmp_ne_u32_e32 vcc, 0, v2
	s_cbranch_vccnz .LBB0_134
	s_add_u32 s0, s11, 0xe0200
	s_addc_u32 s1, s3, 0
	s_add_u32 s6, s11, 0xe0400
	s_addc_u32 s7, s3, 0
	s_add_u32 s8, s11, 0xe0500
	s_addc_u32 s9, s3, 0
	s_add_u32 s12, s11, 0xe0600
	s_addc_u32 s13, s3, 0
	s_add_u32 s14, s11, 0xe0700
	s_addc_u32 s15, s3, 0
	s_add_u32 s16, s11, 0xe0800
	s_addc_u32 s17, s3, 0
	s_add_u32 s18, s11, 0xe0900
	s_addc_u32 s19, s3, 0
	s_add_u32 s20, s11, 0xe0a00
	s_addc_u32 s21, s3, 0
	s_add_u32 s22, s11, 0xe0b00
	s_addc_u32 s23, s3, 0
	s_add_u32 s26, s11, 0xe0c00
	s_addc_u32 s27, s3, 0
	s_add_u32 s28, s11, 0xe0d00
	s_addc_u32 s29, s3, 0
	s_add_u32 s30, s11, 0xe0e00
	s_addc_u32 s31, s3, 0
	s_add_u32 s34, s11, 0xe0f00
	s_addc_u32 s35, s3, 0
	s_add_u32 s38, s11, 0xe1000
	s_addc_u32 s39, s3, 0
	s_add_u32 s40, s11, 0xe1100
	s_addc_u32 s41, s3, 0
	s_add_u32 s42, s11, 0xe1200
	s_addc_u32 s43, s3, 0
	s_add_u32 s46, s11, 0xe1300
	s_mul_i32 s24, s45, s10
	s_addc_u32 s47, s3, 0
	s_mul_i32 s24, s24, s44
	s_mov_b32 s25, 1
	s_mov_b64 s[4:5], 0
	s_waitcnt lgkmcnt(0)
	v_mov_b64_e32 v[0:1], s[6:7]
	v_mov_b64_e32 v[2:3], s[8:9]
	v_mov_b64_e32 v[4:5], s[12:13]
	v_mov_b64_e32 v[6:7], s[14:15]
	v_mov_b64_e32 v[8:9], s[16:17]
	v_mov_b64_e32 v[10:11], s[18:19]
	v_mov_b64_e32 v[12:13], s[20:21]
	v_mov_b64_e32 v[14:15], s[22:23]
	v_mov_b64_e32 v[16:17], s[26:27]
	v_mov_b64_e32 v[18:19], s[28:29]
	v_mov_b64_e32 v[20:21], s[30:31]
	v_mov_b64_e32 v[22:23], s[34:35]
	v_mov_b64_e32 v[24:25], s[38:39]
	v_mov_b64_e32 v[26:27], s[40:41]
	v_mov_b64_e32 v[28:29], s[42:43]
	v_mov_b64_e32 v[30:31], s[46:47]
	s_branch .LBB0_124

; __device__ __forceinline__ unsigned xb_ld(unsigned* p)              { return __hip_atomic_load(p, __ATOMIC_RELAXED, __HIP_MEMORY_SCOPE_AGENT); }
; __device__ __forceinline__ unsigned xb_add(unsigned* p, unsigned v) { return __hip_atomic_fetch_add(p, v, __ATOMIC_RELAXED, __HIP_MEMORY_SCOPE_AGENT); }
; __device__ __forceinline__ void xcd_barrier_complete(unsigned* bar, unsigned x, unsigned& nloc, unsigned& nx) {
;     const unsigned G = gridDim.x * gridDim.y * gridDim.z;
;     unsigned sum, cnt, mine, sp = 0u;
;     for (;;) {
;         sum = 0u; cnt = 0u; mine = 0u;
; #pragma unroll
;         for (unsigned j = 0; j < 16; ++j) { const unsigned c = xb_ld(&bar[XB_XCNT(j)]); sum += c; cnt += (c > 0u) ? 1u : 0u; mine = (j == x) ? c : mine; }
; __device__ __forceinline__ void xcd_barrier(const XcdBarrier& b) {
;     asm volatile("s_waitcnt vmcnt(0)" ::: "memory");
;     __syncthreads();
;     if (threadIdx.x == 0) {
;         unsigned* bar = b.bar;
;         __builtin_amdgcn_s_waitcnt(0);
;         unsigned nloc = b.st[0], nx = b.st[1];
;         if (nloc == 0u) { xcd_barrier_complete(bar, b.x, nloc, nx); b.st[0] = nloc; b.st[1] = nx; }
;         const unsigned old = xb_add(&bar[XB_XSUB(b.x)], 1u);
.LBB0_222:
	v_mov_b32_e32 v0, v205
	s_nop 0
	v_add_u32_e32 v0, 0, v0
	v_add_u32_e32 v0, 0x200c8, v0
	ds_read_b64 v[0:1], v0
	s_getreg_b32 s0, hwreg(HW_REG_XCC_ID, 0, 4)
	s_waitcnt vmcnt(0)
	s_waitcnt lgkmcnt(0)
	s_barrier
	v_readfirstlane_b32 s42, v1
	v_readfirstlane_b32 s43, v0
	s_mov_b64 s[36:37], exec
	v_readlane_b32 s4, v255, 1
	v_readlane_b32 s5, v255, 2
	s_and_b64 s[4:5], s[36:37], s[4:5]
	s_mov_b64 exec, s[4:5]
	s_cbranch_execz .LBB0_266
	buffer_wbl2 sc1
	v_readlane_b32 s1, v255, 47
	s_waitcnt vmcnt(0) expcnt(0) lgkmcnt(0)
	s_and_b32 s48, s0, 15
	v_mov_b32_e32 v0, s1
	ds_read_b32 v2, v0
	v_readlane_b32 s1, v255, 48
	s_waitcnt lgkmcnt(0)
	v_cmp_ne_u32_e32 vcc, 0, v2
	v_mov_b32_e32 v0, s1
	ds_read_b32 v0, v0
	s_cbranch_vccnz .LBB0_237
	s_add_u32 s0, s43, 0xe0200
	s_addc_u32 s1, s42, 0
	s_add_u32 s4, s43, 0xe0400
	s_addc_u32 s5, s42, 0
	s_add_u32 s6, s43, 0xe0500
	s_addc_u32 s7, s42, 0
	s_add_u32 s8, s43, 0xe0600
	s_addc_u32 s9, s42, 0
	s_add_u32 s12, s43, 0xe0700
	s_addc_u32 s13, s42, 0
	s_add_u32 s14, s43, 0xe0800
	s_addc_u32 s15, s42, 0
	s_add_u32 s16, s43, 0xe0900
	s_addc_u32 s17, s42, 0
	s_add_u32 s18, s43, 0xe0a00
	s_addc_u32 s19, s42, 0
	s_add_u32 s20, s43, 0xe0b00
	s_addc_u32 s21, s42, 0
	s_add_u32 s22, s43, 0xe0c00
	s_addc_u32 s23, s42, 0
	s_add_u32 s24, s43, 0xe0d00
	s_addc_u32 s25, s42, 0
	s_add_u32 s26, s43, 0xe0e00
	s_addc_u32 s27, s42, 0
	s_add_u32 s28, s43, 0xe0f00
	s_addc_u32 s29, s42, 0
	s_add_u32 s30, s43, 0xe1000
	s_addc_u32 s31, s42, 0
	s_add_u32 s34, s43, 0xe1100
	s_addc_u32 s35, s42, 0
	s_add_u32 s54, s43, 0xe1200
	s_addc_u32 s55, s42, 0
	s_add_u32 s58, s43, 0xe1300
	s_addc_u32 s59, s42, 0
	s_mov_b32 s49, 1
	s_mov_b64 s[60:61], 0
	s_branch .LBB0_227

; __device__ __forceinline__ unsigned xb_ld(unsigned* p)              { return __hip_atomic_load(p, __ATOMIC_RELAXED, __HIP_MEMORY_SCOPE_AGENT); }
; __device__ __forceinline__ unsigned xb_add(unsigned* p, unsigned v) { return __hip_atomic_fetch_add(p, v, __ATOMIC_RELAXED, __HIP_MEMORY_SCOPE_AGENT); }
; __device__ __forceinline__ void xcd_barrier_complete(unsigned* bar, unsigned x, unsigned& nloc, unsigned& nx) {
;     const unsigned G = gridDim.x * gridDim.y * gridDim.z;
;     unsigned sum, cnt, mine, sp = 0u;
;     for (;;) {
;         sum = 0u; cnt = 0u; mine = 0u;
; #pragma unroll
;         for (unsigned j = 0; j < 16; ++j) { const unsigned c = xb_ld(&bar[XB_XCNT(j)]); sum += c; cnt += (c > 0u) ? 1u : 0u; mine = (j == x) ? c : mine; }
; __device__ __forceinline__ void xcd_barrier(const XcdBarrier& b) {
;     asm volatile("s_waitcnt vmcnt(0)" ::: "memory");
;     __syncthreads();
;     if (threadIdx.x == 0) {
;         unsigned* bar = b.bar;
;         __builtin_amdgcn_s_waitcnt(0);
;         unsigned nloc = b.st[0], nx = b.st[1];
;         if (nloc == 0u) { xcd_barrier_complete(bar, b.x, nloc, nx); b.st[0] = nloc; b.st[1] = nx; }
;         const unsigned old = xb_add(&bar[XB_XSUB(b.x)], 1u);
.LBB0_332:
	v_mov_b32_e32 v0, v205
	s_nop 0
	v_add_u32_e32 v0, 0, v0
	v_add_u32_e32 v0, 0x200c8, v0
	ds_read_b64 v[0:1], v0
	s_getreg_b32 s0, hwreg(HW_REG_XCC_ID, 0, 4)
	s_waitcnt vmcnt(0)
	s_waitcnt vmcnt(0) lgkmcnt(0)
	s_barrier
	v_readfirstlane_b32 s42, v1
	v_readfirstlane_b32 s43, v0
	s_mov_b64 s[36:37], exec
	v_readlane_b32 s4, v255, 1
	v_readlane_b32 s5, v255, 2
	s_and_b64 s[4:5], s[36:37], s[4:5]
	s_mov_b64 exec, s[4:5]
	s_cbranch_execz .LBB0_376
	buffer_wbl2 sc1
	v_readlane_b32 s1, v255, 47
	s_waitcnt vmcnt(0) expcnt(0) lgkmcnt(0)
	s_and_b32 s49, s0, 15
	v_mov_b32_e32 v0, s1
	ds_read_b32 v2, v0
	v_readlane_b32 s1, v255, 48
	s_waitcnt lgkmcnt(0)
	v_cmp_ne_u32_e32 vcc, 0, v2
	v_mov_b32_e32 v0, s1
	ds_read_b32 v0, v0
	s_cbranch_vccnz .LBB0_347
	s_add_u32 s0, s43, 0xe0200
	s_addc_u32 s1, s42, 0
	s_add_u32 s4, s43, 0xe0400
	s_addc_u32 s5, s42, 0
	s_add_u32 s6, s43, 0xe0500
	s_addc_u32 s7, s42, 0
	s_add_u32 s8, s43, 0xe0600
	s_addc_u32 s9, s42, 0
	s_add_u32 s12, s43, 0xe0700
	s_addc_u32 s13, s42, 0
	s_add_u32 s14, s43, 0xe0800
	s_addc_u32 s15, s42, 0
	s_add_u32 s16, s43, 0xe0900
	s_addc_u32 s17, s42, 0
	s_add_u32 s18, s43, 0xe0a00
	s_addc_u32 s19, s42, 0
	s_add_u32 s20, s43, 0xe0b00
	s_addc_u32 s21, s42, 0
	s_add_u32 s22, s43, 0xe0c00
	s_addc_u32 s23, s42, 0
	s_add_u32 s24, s43, 0xe0d00
	s_addc_u32 s25, s42, 0
	s_add_u32 s26, s43, 0xe0e00
	s_addc_u32 s27, s42, 0
	s_add_u32 s28, s43, 0xe0f00
	s_addc_u32 s29, s42, 0
	s_add_u32 s30, s43, 0xe1000
	s_addc_u32 s31, s42, 0
	s_add_u32 s34, s43, 0xe1100
	s_addc_u32 s35, s42, 0
	s_add_u32 s54, s43, 0xe1200
	s_addc_u32 s55, s42, 0
	s_add_u32 s58, s43, 0xe1300
	s_addc_u32 s59, s42, 0
	s_mov_b32 s50, 1
	s_mov_b64 s[60:61], 0
	s_branch .LBB0_337

; __device__ __forceinline__ unsigned xb_ld(unsigned* p)              { return __hip_atomic_load(p, __ATOMIC_RELAXED, __HIP_MEMORY_SCOPE_AGENT); }
; __device__ __forceinline__ unsigned xb_add(unsigned* p, unsigned v) { return __hip_atomic_fetch_add(p, v, __ATOMIC_RELAXED, __HIP_MEMORY_SCOPE_AGENT); }
; __device__ __forceinline__ void xcd_barrier_complete(unsigned* bar, unsigned x, unsigned& nloc, unsigned& nx) {
;     const unsigned G = gridDim.x * gridDim.y * gridDim.z;
;     unsigned sum, cnt, mine, sp = 0u;
;     for (;;) {
;         sum = 0u; cnt = 0u; mine = 0u;
; #pragma unroll
;         for (unsigned j = 0; j < 16; ++j) { const unsigned c = xb_ld(&bar[XB_XCNT(j)]); sum += c; cnt += (c > 0u) ? 1u : 0u; mine = (j == x) ? c : mine; }
; __device__ __forceinline__ void xcd_barrier(const XcdBarrier& b) {
;     asm volatile("s_waitcnt vmcnt(0)" ::: "memory");
;     __syncthreads();
;     if (threadIdx.x == 0) {
;         unsigned* bar = b.bar;
;         __builtin_amdgcn_s_waitcnt(0);
;         unsigned nloc = b.st[0], nx = b.st[1];
;         if (nloc == 0u) { xcd_barrier_complete(bar, b.x, nloc, nx); b.st[0] = nloc; b.st[1] = nx; }
;         const unsigned old = xb_add(&bar[XB_XSUB(b.x)], 1u);
.LBB0_494:
	v_mov_b32_e32 v0, v205
	s_nop 0
	v_add_u32_e32 v0, 0, v0
	v_add_u32_e32 v0, 0x200c8, v0
	ds_read_b64 v[0:1], v0
	s_getreg_b32 s0, hwreg(HW_REG_XCC_ID, 0, 4)
	s_waitcnt vmcnt(0)
	s_waitcnt lgkmcnt(0)
	s_barrier
	v_readfirstlane_b32 s4, v1
	v_readfirstlane_b32 s5, v0
	s_mov_b64 s[54:55], exec
	v_readlane_b32 s6, v255, 1
	v_readlane_b32 s7, v255, 2
	s_and_b64 s[6:7], s[54:55], s[6:7]
	s_mov_b64 exec, s[6:7]
	s_cbranch_execz .LBB0_538
	buffer_wbl2 sc1
	v_readlane_b32 s1, v255, 47
	s_waitcnt vmcnt(0) expcnt(0) lgkmcnt(0)
	s_and_b32 s42, s0, 15
	v_mov_b32_e32 v0, s1
	ds_read_b32 v2, v0
	v_readlane_b32 s1, v255, 48
	s_waitcnt lgkmcnt(0)
	v_cmp_ne_u32_e32 vcc, 0, v2
	v_mov_b32_e32 v0, s1
	ds_read_b32 v0, v0
	s_cbranch_vccnz .LBB0_509
	s_add_u32 s0, s5, 0xe0200
	s_addc_u32 s1, s4, 0
	s_add_u32 s6, s5, 0xe0400
	s_addc_u32 s7, s4, 0
	s_add_u32 s8, s5, 0xe0500
	s_addc_u32 s9, s4, 0
	s_add_u32 s12, s5, 0xe0600
	s_addc_u32 s13, s4, 0
	s_add_u32 s14, s5, 0xe0700
	s_addc_u32 s15, s4, 0
	s_add_u32 s16, s5, 0xe0800
	s_addc_u32 s17, s4, 0
	s_add_u32 s18, s5, 0xe0900
	s_addc_u32 s19, s4, 0
	s_add_u32 s20, s5, 0xe0a00
	s_addc_u32 s21, s4, 0
	s_add_u32 s22, s5, 0xe0b00
	s_addc_u32 s23, s4, 0
	s_add_u32 s24, s5, 0xe0c00
	s_addc_u32 s25, s4, 0
	s_add_u32 s26, s5, 0xe0d00
	s_addc_u32 s27, s4, 0
	s_add_u32 s28, s5, 0xe0e00
	s_addc_u32 s29, s4, 0
	s_add_u32 s30, s5, 0xe0f00
	s_addc_u32 s31, s4, 0
	s_add_u32 s34, s5, 0xe1000
	s_addc_u32 s35, s4, 0
	s_add_u32 s36, s5, 0xe1100
	s_addc_u32 s37, s4, 0
	s_add_u32 s58, s5, 0xe1200
	s_addc_u32 s59, s4, 0
	s_add_u32 s60, s5, 0xe1300
	s_addc_u32 s61, s4, 0
	s_mov_b32 s43, 1
	s_mov_b64 s[62:63], 0
	s_branch .LBB0_499

; __device__ __forceinline__ unsigned xb_ld(unsigned* p)              { return __hip_atomic_load(p, __ATOMIC_RELAXED, __HIP_MEMORY_SCOPE_AGENT); }
; __device__ __forceinline__ unsigned xb_add(unsigned* p, unsigned v) { return __hip_atomic_fetch_add(p, v, __ATOMIC_RELAXED, __HIP_MEMORY_SCOPE_AGENT); }
; __device__ __forceinline__ void xcd_barrier_complete(unsigned* bar, unsigned x, unsigned& nloc, unsigned& nx) {
;     const unsigned G = gridDim.x * gridDim.y * gridDim.z;
;     unsigned sum, cnt, mine, sp = 0u;
;     for (;;) {
;         sum = 0u; cnt = 0u; mine = 0u;
; #pragma unroll
;         for (unsigned j = 0; j < 16; ++j) { const unsigned c = xb_ld(&bar[XB_XCNT(j)]); sum += c; cnt += (c > 0u) ? 1u : 0u; mine = (j == x) ? c : mine; }
; __device__ __forceinline__ void xcd_barrier(const XcdBarrier& b) {
;     asm volatile("s_waitcnt vmcnt(0)" ::: "memory");
;     __syncthreads();
;     if (threadIdx.x == 0) {
;         unsigned* bar = b.bar;
;         __builtin_amdgcn_s_waitcnt(0);
;         unsigned nloc = b.st[0], nx = b.st[1];
;         if (nloc == 0u) { xcd_barrier_complete(bar, b.x, nloc, nx); b.st[0] = nloc; b.st[1] = nx; }
;         const unsigned old = xb_add(&bar[XB_XSUB(b.x)], 1u);
.LBB0_613:
	v_mov_b32_e32 v0, v205
	s_nop 0
	v_add_u32_e32 v0, 0, v0
	v_add_u32_e32 v0, 0x200c8, v0
	s_waitcnt lgkmcnt(0)
	ds_read_b64 v[0:1], v0
	s_getreg_b32 s0, hwreg(HW_REG_XCC_ID, 0, 4)
	s_waitcnt vmcnt(0)
	s_waitcnt lgkmcnt(0)
	s_barrier
	v_readfirstlane_b32 s50, v1
	v_readfirstlane_b32 s72, v0
	s_mov_b64 s[36:37], exec
	v_readlane_b32 s4, v255, 1
	v_readlane_b32 s5, v255, 2
	s_and_b64 s[4:5], s[36:37], s[4:5]
	s_mov_b64 exec, s[4:5]
	s_cbranch_execz .LBB0_165
	buffer_wbl2 sc1
	v_readlane_b32 s1, v255, 47
	s_waitcnt vmcnt(0) expcnt(0) lgkmcnt(0)
	s_and_b32 s73, s0, 15
	v_mov_b32_e32 v0, s1
	ds_read_b32 v2, v0
	v_readlane_b32 s1, v255, 48
	s_waitcnt lgkmcnt(0)
	v_cmp_ne_u32_e32 vcc, 0, v2
	v_mov_b32_e32 v0, s1
	ds_read_b32 v0, v0
	s_cbranch_vccnz .LBB0_629
	s_add_u32 s0, s72, 0xe0200
	s_addc_u32 s1, s50, 0
	s_add_u32 s4, s72, 0xe0400
	s_addc_u32 s5, s50, 0
	s_add_u32 s6, s72, 0xe0500
	s_addc_u32 s7, s50, 0
	s_add_u32 s8, s72, 0xe0600
	s_addc_u32 s9, s50, 0
	s_add_u32 s12, s72, 0xe0700
	s_addc_u32 s13, s50, 0
	s_add_u32 s14, s72, 0xe0800
	s_addc_u32 s15, s50, 0
	s_add_u32 s16, s72, 0xe0900
	s_addc_u32 s17, s50, 0
	s_add_u32 s18, s72, 0xe0a00
	s_addc_u32 s19, s50, 0
	s_add_u32 s20, s72, 0xe0b00
	s_addc_u32 s21, s50, 0
	s_add_u32 s22, s72, 0xe0c00
	s_addc_u32 s23, s50, 0
	s_add_u32 s24, s72, 0xe0d00
	s_addc_u32 s25, s50, 0
	s_add_u32 s26, s72, 0xe0e00
	s_addc_u32 s27, s50, 0
	s_add_u32 s28, s72, 0xe0f00
	s_addc_u32 s29, s50, 0
	s_add_u32 s30, s72, 0xe1000
	s_addc_u32 s31, s50, 0
	s_add_u32 s34, s72, 0xe1100
	s_addc_u32 s35, s50, 0
	s_add_u32 s42, s72, 0xe1200
	s_addc_u32 s43, s50, 0
	s_add_u32 s54, s72, 0xe1300
	s_addc_u32 s55, s50, 0
	s_mov_b32 s74, 1
	s_mov_b64 s[58:59], 0
	s_branch .LBB0_618
